# attention fast loop: static priority on the younger half of the workgroup (waves 4-7) instead of waves 0-3
# speedup vs baseline: 1.0087x; 1.0019x over previous
; #define LAS __attribute__((address_space(3)))
; __device__ __forceinline__ int opaque_tid() { int t = threadIdx.x; asm volatile("" : "+v"(t)); return t; }
; __device__ __forceinline__ int v_st_nat(int k, int c) { return ((k >> 3) * 2 + (c >> 5)) * 512 + ((k & 7) * 32 + (c & 31)) * 2; }
; __device__ __forceinline__ int v_rd_base(int lane) { return ((lane & 3) << 3) | (((lane >> 2) & 3) << 6) | (((lane >> 4) & 1) << 5) | (((lane >> 5) & 1) << 8); }
; #define AT_LOAD(K0, K1, V0, V1, T) do { const size_t e_ = (size_t)(128 * (T) + sr) * 64 + sc; \
;         K0 = *(const bf16x8*)(kcp + e_); V0 = *(const bf16x8*)(vcp + e_); K1 = *(const bf16x8*)(kcp + e_ + 64 * 64); V1 = *(const bf16x8*)(vcp + e_ + 64 * 64); } while (0)
; #define AT_STORE(K0, K1, V0, V1, BUF) do { *(LAS bf16x8*)(lds + AT_K + (BUF) * AT_KB + kst0) = K0; *(LAS bf16x8*)(lds + AT_K + (BUF) * AT_KB + kst1) = K1; \
;         *(LAS bf16x8*)(lds + AT_V + (BUF) * AT_VB + vst0) = V0; *(LAS bf16x8*)(lds + AT_V + (BUF) * AT_VB + vst1) = V1; } while (0)
; template <int VAR>
; __device__ __forceinline__ void attn_unit(const Args& a, int l, int b, int h, int qrow0  , bool ctxu, const bf16* Z, bf16* Y, LAS unsigned char* lds) {
;     const int tid = opaque_tid(), lane = tid & 63, wave = __builtin_amdgcn_readfirstlane(tid >> 6), r32 = lane & 31, hi = lane >> 5;
;     const int comp = wave >> 2, wq = wave & 3;
;     const int NT = ctxu ? 2 : 66;
;     const bf16* kcp = (const bf16*)(a.ws + WS_KC) + (size_t)(b * 4 + h) * 8448 * 64; const bf16* vcp = (const bf16*)(a.ws + WS_VC) + (size_t)(b * 4 + h) * 8448 * 64;
;     bf16x8 q0, q1;
;     { const bf16* qp = Z + (size_t)(qrow0 + wq * 32 + r32) * DIN + 512 + h * 64 + comp * 32 + hi * 8; q0 = *(const bf16x8*)(qp); q1 = *(const bf16x8*)(qp + 16); }
;     const int sr = tid >> 3, sc = (tid & 7) * 8;
;     const int kst0 = sr * 144 + sc * 2, kst1 = kst0 + 64 * 144, vst0 = v_st_nat(sr, sc), vst1 = v_st_nat(sr + 64, sc);
;     const int vb0 = (int)(unsigned)(uintptr_t)(lds + AT_V) + v_rd_base(lane);
;     LAS float* wsf = (LAS float*)(lds + AT_WS) + wave * 64;
;     f32x16 negm = f32x16{}, o0 = f32x16{}, o1 = f32x16{}, lacc = f32x16{};
;     float m = 0.f;
;     bf16x8 ka0, ka1, va0, va1, kb0, kb1, vb0_, vb1_;
;     ...
;     AT_LOAD(ka0, ka1, va0, va1, 0); AT_LOAD(kb0, kb1, vb0_, vb1_, 1); AT_STORE(ka0, ka1, va0, va1, 0);
;     const LAS unsigned char* Kb0 = lds + AT_K + comp * 64;
.LBB0_431:
	v_mov_b32_e32 v79, 0
	v_readfirstlane_b32 s36, v230
	v_readfirstlane_b32 s37, v231
	s_mov_b32 s94, 1
	s_mov_b32 s95, 1
	s_mov_b32 s33, 0
	s_lshr_b32 s50, s29, 6
	s_lshl_b32 s51, s50, 10
	s_lshl_b32 s93, s50, 8
	s_lshl_b32 s50, s50, 3
	v_lshrrev_b32_e32 v132, 3, v227
	v_add_u32_e32 v132, s50, v132
	v_bfe_u32 v133, v132, 1, 3
	v_and_b32_e32 v134, 7, v227
	v_xor_b32_e32 v134, v134, v133
	v_lshlrev_b32_e32 v132, 7, v132
	v_lshl_or_b32 v158, v134, 4, v132
	v_add_u32_e32 v159, 0x2000, v158
	v_bfe_u32 v132, v227, 2, 3
	v_add_u32_e32 v132, s50, v132
	v_lshrrev_b32_e32 v133, 5, v227
	v_and_b32_e32 v134, 3, v227
	v_lshlrev_b32_e32 v133, 6, v133
	v_lshl_or_b32 v133, v134, 4, v133
	v_lshl_or_b32 v160, v132, 7, v133
	v_add_u32_e32 v161, 0x2000, v160
	s_lshl_b32 s50, s8, 2
	v_add_u32_e32 v132, s50, v248
	v_bfe_u32 v133, v247, 1, 3
	v_xor_b32_e32 v132, v132, v133
	v_lshlrev_b32_e32 v133, 7, v247
	v_lshl_or_b32 v144, v132, 4, v133
	v_xor_b32_e32 v145, 32, v144
	v_add_u32_e32 v146, 0x3000, v249
	s_add_u32 s93, s93, 0x19800
	v_lshlrev_b32_e32 v132, 2, v247
	v_add_u32_e32 v148, s93, v132
	v_lshlrev_b32_e32 v132, 4, v248
	v_add_u32_e32 v147, s93, v132
	v_mov_b32_e32 v132, 0x19880
	v_mov_b32_e32 v133, 0
	ds_write_b32 v132, v133
	v_mov_b32_e32 v80, 0
	v_mov_b32_e32 v200, 0
	v_mov_b32_e32 v81, 0
	v_mov_b32_e32 v201, 0
	v_mov_b32_e32 v82, 0
	v_mov_b32_e32 v202, 0
	v_mov_b32_e32 v83, 0
	v_mov_b32_e32 v203, 0
	v_mov_b32_e32 v84, 0
	v_mov_b32_e32 v204, 0
	v_mov_b32_e32 v85, 0
	v_mov_b32_e32 v205, 0
	v_mov_b32_e32 v86, 0
	v_mov_b32_e32 v206, 0
	v_mov_b32_e32 v87, 0
	v_mov_b32_e32 v207, 0
	v_mov_b32_e32 v88, 0
	v_mov_b32_e32 v208, 0
	v_mov_b32_e32 v89, 0
	v_mov_b32_e32 v209, 0
	v_mov_b32_e32 v90, 0
	v_mov_b32_e32 v210, 0
	v_mov_b32_e32 v91, 0
	v_mov_b32_e32 v211, 0
	v_mov_b32_e32 v92, 0
	v_mov_b32_e32 v212, 0
	v_mov_b32_e32 v93, 0
	v_mov_b32_e32 v213, 0
	v_mov_b32_e32 v94, 0
	v_mov_b32_e32 v214, 0
	v_mov_b32_e32 v95, 0
	v_mov_b32_e32 v215, 0
	v_mov_b32_e32 v128, 0
	v_mov_b32_e32 v129, 0
	v_mov_b32_e32 v130, 0
	v_mov_b32_e32 v131, 0
	v_mov_b32_e32 v149, 0
	s_sub_u32 s36, s36, s51
	s_subb_u32 s37, s37, 0
	s_add_u32 s48, s36, 0x1d200000
	s_addc_u32 s49, s37, 0
	s_add_u32 s36, s36, 0x1c000000
	s_addc_u32 s37, s37, 0
	s_cmp_eq_u32 s8, 1
	s_cbranch_scc0 .Lat_noprioF
	s_setprio 1

; #define LAS __attribute__((address_space(3)))
; __device__ __forceinline__ int opaque_tid() { int t = threadIdx.x; asm volatile("" : "+v"(t)); return t; }
; __device__ __forceinline__ int v_st_nat(int k, int c) { return ((k >> 3) * 2 + (c >> 5)) * 512 + ((k & 7) * 32 + (c & 31)) * 2; }
; __device__ __forceinline__ int v_rd_base(int lane) { return ((lane & 3) << 3) | (((lane >> 2) & 3) << 6) | (((lane >> 4) & 1) << 5) | (((lane >> 5) & 1) << 8); }
; #define AT_LOAD(K0, K1, V0, V1, T) do { const size_t e_ = (size_t)(128 * (T) + sr) * 64 + sc; \
;         K0 = *(const bf16x8*)(kcp + e_); V0 = *(const bf16x8*)(vcp + e_); K1 = *(const bf16x8*)(kcp + e_ + 64 * 64); V1 = *(const bf16x8*)(vcp + e_ + 64 * 64); } while (0)
; #define AT_STORE(K0, K1, V0, V1, BUF) do { *(LAS bf16x8*)(lds + AT_K + (BUF) * AT_KB + kst0) = K0; *(LAS bf16x8*)(lds + AT_K + (BUF) * AT_KB + kst1) = K1; \
;         *(LAS bf16x8*)(lds + AT_V + (BUF) * AT_VB + vst0) = V0; *(LAS bf16x8*)(lds + AT_V + (BUF) * AT_VB + vst1) = V1; } while (0)
; template <int VAR>
; __device__ __forceinline__ void attn_unit(const Args& a, int l, int b, int h, int qrow0  , bool ctxu, const bf16* Z, bf16* Y, LAS unsigned char* lds) {
;     const int tid = opaque_tid(), lane = tid & 63, wave = __builtin_amdgcn_readfirstlane(tid >> 6), r32 = lane & 31, hi = lane >> 5;
;     const int comp = wave >> 2, wq = wave & 3;
;     const int NT = ctxu ? 2 : 66;
;     const bf16* kcp = (const bf16*)(a.ws + WS_KC) + (size_t)(b * 4 + h) * 8448 * 64; const bf16* vcp = (const bf16*)(a.ws + WS_VC) + (size_t)(b * 4 + h) * 8448 * 64;
;     bf16x8 q0, q1;
;     { const bf16* qp = Z + (size_t)(qrow0 + wq * 32 + r32) * DIN + 512 + h * 64 + comp * 32 + hi * 8; q0 = *(const bf16x8*)(qp); q1 = *(const bf16x8*)(qp + 16); }
;     const int sr = tid >> 3, sc = (tid & 7) * 8;
;     const int kst0 = sr * 144 + sc * 2, kst1 = kst0 + 64 * 144, vst0 = v_st_nat(sr, sc), vst1 = v_st_nat(sr + 64, sc);
;     const int vb0 = (int)(unsigned)(uintptr_t)(lds + AT_V) + v_rd_base(lane);
;     LAS float* wsf = (LAS float*)(lds + AT_WS) + wave * 64;
;     f32x16 negm = f32x16{}, o0 = f32x16{}, o1 = f32x16{}, lacc = f32x16{};
;     float m = 0.f;
;     bf16x8 ka0, ka1, va0, va1, kb0, kb1, vb0_, vb1_;
;     ...
;     AT_LOAD(ka0, ka1, va0, va1, 0); AT_LOAD(kb0, kb1, vb0_, vb1_, 1); AT_STORE(ka0, ka1, va0, va1, 0);
;     const LAS unsigned char* Kb0 = lds + AT_K + comp * 64;
.Lat_safe_entry:
	s_barrier
	v_mov_b32_e32 v0, 0
	v_mov_b32_e32 v1, 0
	v_mov_b32_e32 v2, 0
	v_mov_b32_e32 v3, 0
	v_mov_b32_e32 v4, 0
	v_mov_b32_e32 v5, 0
	v_mov_b32_e32 v6, 0
	v_mov_b32_e32 v7, 0
	v_mov_b32_e32 v8, 0
	v_mov_b32_e32 v9, 0
	v_mov_b32_e32 v10, 0
	v_mov_b32_e32 v11, 0
	v_mov_b32_e32 v12, 0
	v_mov_b32_e32 v13, 0
	v_mov_b32_e32 v14, 0
	v_mov_b32_e32 v15, 0
	v_mov_b32_e32 v16, 0
	v_mov_b32_e32 v17, 0
	v_mov_b32_e32 v18, 0
	v_mov_b32_e32 v19, 0
	v_mov_b32_e32 v20, 0
	v_mov_b32_e32 v21, 0
	v_mov_b32_e32 v22, 0
	v_mov_b32_e32 v23, 0
	v_mov_b32_e32 v24, 0
	v_mov_b32_e32 v25, 0
	v_mov_b32_e32 v26, 0
	v_mov_b32_e32 v27, 0
	v_mov_b32_e32 v28, 0
	v_mov_b32_e32 v29, 0
	v_mov_b32_e32 v30, 0
	v_mov_b32_e32 v31, 0
	v_mov_b32_e32 v32, 0
	v_mov_b32_e32 v33, 0
	v_mov_b32_e32 v34, 0
	v_mov_b32_e32 v35, 0
	v_mov_b32_e32 v36, 0
	v_mov_b32_e32 v37, 0
	v_mov_b32_e32 v38, 0
	v_mov_b32_e32 v39, 0
	v_mov_b32_e32 v40, 0
	v_mov_b32_e32 v41, 0
	v_mov_b32_e32 v42, 0
	v_mov_b32_e32 v43, 0
	v_mov_b32_e32 v44, 0
	v_mov_b32_e32 v45, 0
	v_mov_b32_e32 v46, 0
	v_mov_b32_e32 v47, 0
	v_mov_b32_e32 v64, 0
	v_mov_b32_e32 v65, 0
	v_mov_b32_e32 v66, 0
	v_mov_b32_e32 v67, 0
	v_mov_b32_e32 v68, 0
	v_mov_b32_e32 v69, 0
	v_mov_b32_e32 v70, 0
	v_mov_b32_e32 v71, 0
	v_mov_b32_e32 v72, 0
	v_mov_b32_e32 v73, 0
	v_mov_b32_e32 v74, 0
	v_mov_b32_e32 v75, 0
	v_mov_b32_e32 v76, 0
	v_mov_b32_e32 v77, 0
	v_mov_b32_e32 v78, 0
	v_mov_b32_e32 v79, 0
	v_mov_b32_e32 v234, 0
	v_mov_b32_e32 v79, 0
	v_readfirstlane_b32 s36, v230
	v_readfirstlane_b32 s37, v231
	s_mov_b32 s94, 1
	s_mov_b32 s95, 1
	s_mov_b32 s33, 0
	s_lshr_b32 s50, s29, 6
	s_lshl_b32 s51, s50, 10
	s_lshl_b32 s93, s50, 8
	s_lshl_b32 s50, s50, 3
	v_lshrrev_b32_e32 v132, 3, v227
	v_add_u32_e32 v132, s50, v132
	v_bfe_u32 v133, v132, 1, 3
	v_and_b32_e32 v134, 7, v227
	v_xor_b32_e32 v134, v134, v133
	v_lshlrev_b32_e32 v132, 7, v132
	v_lshl_or_b32 v158, v134, 4, v132
	v_add_u32_e32 v159, 0x2000, v158
	v_bfe_u32 v132, v227, 2, 3
	v_add_u32_e32 v132, s50, v132
	v_lshrrev_b32_e32 v133, 5, v227
	v_and_b32_e32 v134, 3, v227
	v_lshlrev_b32_e32 v133, 6, v133
	v_lshl_or_b32 v133, v134, 4, v133
	v_lshl_or_b32 v160, v132, 7, v133
	v_add_u32_e32 v161, 0x2000, v160
	s_lshl_b32 s50, s8, 2
	v_add_u32_e32 v132, s50, v248
	v_bfe_u32 v133, v247, 1, 3
	v_xor_b32_e32 v132, v132, v133
	v_lshlrev_b32_e32 v133, 7, v247
	v_lshl_or_b32 v144, v132, 4, v133
	v_xor_b32_e32 v145, 32, v144
	v_add_u32_e32 v146, 0x3000, v249
	s_add_u32 s93, s93, 0x19800
	v_lshlrev_b32_e32 v132, 2, v247
	v_add_u32_e32 v148, s93, v132
	v_lshlrev_b32_e32 v132, 4, v248
	v_add_u32_e32 v147, s93, v132
	v_mov_b32_e32 v132, 0x19880
	v_mov_b32_e32 v133, 0
	ds_write_b32 v132, v133
	v_mov_b32_e32 v80, 0
	v_mov_b32_e32 v200, 0
	v_mov_b32_e32 v81, 0
	v_mov_b32_e32 v201, 0
	v_mov_b32_e32 v82, 0
	v_mov_b32_e32 v202, 0
	v_mov_b32_e32 v83, 0
	v_mov_b32_e32 v203, 0
	v_mov_b32_e32 v84, 0
	v_mov_b32_e32 v204, 0
	v_mov_b32_e32 v85, 0
	v_mov_b32_e32 v205, 0
	v_mov_b32_e32 v86, 0
	v_mov_b32_e32 v206, 0
	v_mov_b32_e32 v87, 0
	v_mov_b32_e32 v207, 0
	v_mov_b32_e32 v88, 0
	v_mov_b32_e32 v208, 0
	v_mov_b32_e32 v89, 0
	v_mov_b32_e32 v209, 0
	v_mov_b32_e32 v90, 0
	v_mov_b32_e32 v210, 0
	v_mov_b32_e32 v91, 0
	v_mov_b32_e32 v211, 0
	v_mov_b32_e32 v92, 0
	v_mov_b32_e32 v212, 0
	v_mov_b32_e32 v93, 0
	v_mov_b32_e32 v213, 0
	v_mov_b32_e32 v94, 0
	v_mov_b32_e32 v214, 0
	v_mov_b32_e32 v95, 0
	v_mov_b32_e32 v215, 0
	v_mov_b32_e32 v128, 0
	v_mov_b32_e32 v129, 0
	v_mov_b32_e32 v130, 0
	v_mov_b32_e32 v131, 0
	v_mov_b32_e32 v149, 0
	s_sub_u32 s36, s36, s51
	s_subb_u32 s37, s37, 0
	s_add_u32 s48, s36, 0x1d200000
	s_addc_u32 s49, s37, 0
	s_add_u32 s36, s36, 0x1c000000
	s_addc_u32 s37, s37, 0
	s_cmp_eq_u32 s8, 1
	s_cbranch_scc0 .Lat_noprioS
	s_setprio 1
